# v58 + MLA steady step: end-of-step wait+barrier moved in front of the last two P.V MFMAs, first six K fragments of the next tile read behind it (hidden under those MFMAs)
# baseline (speedup 1.0000x reference)
.Lmla2_reads:
	ds_read_b128 v[82:85], v67
	ds_read_b128 v[158:161], v67 offset:2048
	ds_read_b128 v[162:165], v66
	ds_read_b128 v[150:153], v66 offset:2048
	ds_read_b128 v[146:149], v67 offset:4096
	ds_read_b128 v[142:145], v67 offset:6144
.Lmla2_reads7:
	ds_read_b128 v[138:141], v66 offset:4096
	ds_read_b128 v[134:137], v66 offset:6144
	ds_read_b128 v[130:133], v67 offset:8192
	ds_read_b128 v[126:129], v67 offset:10240
	ds_read_b128 v[122:125], v66 offset:8192
	ds_read_b128 v[154:157], v66 offset:10240
	s_waitcnt lgkmcnt(11)
	v_mfma_f32_32x32x16_bf16 v[66:81], v[82:85], v[98:101], v[50:65]
	s_lshl_b32 s58, s49, 13
	s_waitcnt lgkmcnt(10)
	v_mfma_f32_32x32x16_bf16 v[82:97], v[158:161], v[98:101], v[50:65]
	v_add_u32_e32 v158, s58, v183
	s_add_u32 s26, s54, s24
	s_addc_u32 s27, s55, s25
	s_xor_b32 s57, s49, 1
	s_mul_i32 s56, s57, 0x3000
	s_add_i32 s51, s56, s38
	s_mov_b32 s98, m0
	s_mov_b32 m0, s51
	s_nop 0
	global_load_lds_dwordx4 v1, s[26:27]
	s_mov_b32 m0, s98
	s_and_b64 vcc, exec, s[8:9]
	s_cbranch_vccnz .LBB0_1478
	s_add_i32 s26, s56, s39
	s_mov_b32 s27, m0
	s_mov_b32 m0, s26
	s_nop 0
	global_load_lds_dwordx4 v180, s[22:23]
	s_mov_b32 m0, s27

.LBB0_1482:
	v_exp_f32_e32 v66, v66
	v_exp_f32_e32 v67, v67
	v_exp_f32_e32 v68, v68
	v_exp_f32_e32 v69, v69
	v_exp_f32_e32 v70, v70
	v_exp_f32_e32 v71, v71
	v_exp_f32_e32 v72, v72
	v_exp_f32_e32 v73, v73
	v_pk_add_f32 v[154:155], v[66:67], v[68:69]
	v_pk_add_f32 v[156:157], v[70:71], v[72:73]
	v_pk_add_f32 v[158:159], v[154:155], v[156:157]
	v_cvt_pk_bf16_f32 v66, v66, v67
	v_cvt_pk_bf16_f32 v67, v68, v69
	v_cvt_pk_bf16_f32 v68, v70, v71
	v_cvt_pk_bf16_f32 v69, v72, v73
	v_exp_f32_e32 v74, v74
	v_exp_f32_e32 v75, v75
	v_mfma_f32_32x32x16_bf16 v[18:33], v[66:69], v[150:153], v[18:33]
	v_exp_f32_e32 v76, v76
	v_exp_f32_e32 v77, v77
	v_exp_f32_e32 v78, v78
	s_waitcnt lgkmcnt(6)
	v_mfma_f32_32x32x16_bf16 v[34:49], v[66:69], v[134:137], v[34:49]
	v_exp_f32_e32 v79, v79
	v_exp_f32_e32 v80, v80
	v_exp_f32_e32 v81, v81
	v_pk_add_f32 v[154:155], v[74:75], v[76:77]
	v_pk_add_f32 v[156:157], v[78:79], v[80:81]
	v_pk_add_f32 v[160:161], v[154:155], v[156:157]
	v_cvt_pk_bf16_f32 v70, v74, v75
	v_cvt_pk_bf16_f32 v71, v76, v77
	v_cvt_pk_bf16_f32 v72, v78, v79
	v_cvt_pk_bf16_f32 v73, v80, v81
	v_exp_f32_e32 v82, v82
	v_exp_f32_e32 v83, v83
	v_mfma_f32_32x32x16_bf16 v[18:33], v[70:73], v[146:149], v[18:33]
	v_exp_f32_e32 v84, v84
	v_exp_f32_e32 v85, v85
	v_exp_f32_e32 v86, v86
	s_waitcnt lgkmcnt(4)
	v_mfma_f32_32x32x16_bf16 v[34:49], v[70:73], v[130:133], v[34:49]
	v_exp_f32_e32 v87, v87
	v_exp_f32_e32 v88, v88
	v_exp_f32_e32 v89, v89
	v_pk_add_f32 v[154:155], v[82:83], v[84:85]
	v_pk_add_f32 v[156:157], v[86:87], v[88:89]
	v_pk_add_f32 v[162:163], v[154:155], v[156:157]
	v_cvt_pk_bf16_f32 v74, v82, v83
	v_cvt_pk_bf16_f32 v75, v84, v85
	v_cvt_pk_bf16_f32 v76, v86, v87
	v_cvt_pk_bf16_f32 v77, v88, v89
	v_exp_f32_e32 v90, v90
	v_exp_f32_e32 v91, v91
	v_mfma_f32_32x32x16_bf16 v[18:33], v[74:77], v[142:145], v[18:33]
	v_exp_f32_e32 v92, v92
	v_exp_f32_e32 v93, v93
	v_exp_f32_e32 v94, v94
	s_waitcnt lgkmcnt(2)
	v_mfma_f32_32x32x16_bf16 v[34:49], v[74:77], v[126:129], v[34:49]
	v_exp_f32_e32 v95, v95
	v_exp_f32_e32 v96, v96
	v_exp_f32_e32 v97, v97
	v_pk_add_f32 v[154:155], v[90:91], v[92:93]
	v_pk_add_f32 v[156:157], v[94:95], v[96:97]
	v_pk_add_f32 v[164:165], v[154:155], v[156:157]
	v_cvt_pk_bf16_f32 v78, v90, v91
	v_cvt_pk_bf16_f32 v79, v92, v93
	v_cvt_pk_bf16_f32 v80, v94, v95
	v_cvt_pk_bf16_f32 v81, v96, v97
	v_pk_add_f32 v[158:159], v[158:159], v[160:161]
	v_pk_add_f32 v[162:163], v[162:163], v[164:165]
	v_pk_add_f32 v[158:159], v[158:159], v[162:163]
	v_add_u32_e32 v66, s56, v182
	v_add_f32_e32 v158, v158, v159
	v_add_u32_e32 v67, v66, v184
	v_add_f32_e32 v173, v173, v158
	v_add_u32_e32 v66, v66, v189
	s_add_u32 s24, s24, 0x10000
	s_addc_u32 s25, s25, 0
	s_add_u32 s22, s22, 0x1000
	s_addc_u32 s23, s23, 0
	s_cmp_eq_u32 s24, 0x200000
	s_waitcnt vmcnt(0) lgkmcnt(0)
	s_barrier
	s_cbranch_scc1 .Lmla2_last
	ds_read_b128 v[82:85], v67
	ds_read_b128 v[158:161], v67 offset:2048
	ds_read_b128 v[162:165], v66
	ds_read_b128 v[150:153], v66 offset:2048
	ds_read_b128 v[146:149], v67 offset:4096
	ds_read_b128 v[142:145], v67 offset:6144
	v_mfma_f32_32x32x16_bf16 v[18:33], v[78:81], v[138:141], v[18:33]
	v_mfma_f32_32x32x16_bf16 v[34:49], v[78:81], v[122:125], v[34:49]
	s_mov_b32 s49, s57
	s_mul_i32 s52, s49, 0x3000
	s_branch .Lmla2_reads7
.Lmla2_last:
	v_mfma_f32_32x32x16_bf16 v[18:33], v[78:81], v[138:141], v[18:33]
	v_mfma_f32_32x32x16_bf16 v[34:49], v[78:81], v[122:125], v[34:49]
	s_branch .LBB0_1484
